# direction check: static attention priority on the older wave half (waves 0-3) instead of the younger, otherwise v40
# speedup vs baseline: 1.0069x; 1.0069x over previous
.LBB0_823:
	s_cmp_lt_i32 s28, 7
	s_cselect_b64 s[0:1], -1, 0
	s_and_b64 s[8:9], s[0:1], s[6:7]
	s_andn2_b64 vcc, exec, s[8:9]
	s_cbranch_vccnz .LBB0_909
	s_cmp_ge_u32 s76, 4
	s_cbranch_scc1 .Latt_prio_skip
	s_setprio 1
